# phase 0 weight conversion hand-written: software-pipelined (3 tiles in flight per block), tile order changed so neighbouring blocks read neighbouring 256-B segments of the same source rows
# speedup vs baseline: 1.0066x; 1.0066x over previous
.LBB0_8:
	s_or_b64 exec, exec, s[4:5]
	s_cmpk_gt_i32 s2, 0xbf
	s_cbranch_scc1 .LBB0_68
	s_mov_b64 s[4:5], 0xf0c3700
	v_lshl_add_u64 v[48:49], v[46:47], 0, s[4:5]
	s_mov_b64 s[4:5], 0xf183700
	v_lshl_add_u64 v[50:51], v[46:47], 0, s[4:5]
	s_mov_b64 s[4:5], 0x2080000
	v_lshl_add_u64 v[52:53], v[46:47], 0, s[4:5]
	s_mov_b64 s[4:5], 0x1c80000
	v_lshl_add_u64 v[54:55], v[46:47], 0, s[4:5]
	s_mov_b64 s[4:5], 0x2480000
	v_lshl_add_u64 v[56:57], v[46:47], 0, s[4:5]
	s_mov_b64 s[4:5], 0x24a0040
	s_add_u32 s12, s0, 0xf0
	v_lshl_add_u64 v[58:59], v[46:47], 0, s[4:5]
	s_mov_b64 s[4:5], 0x249e000
	s_addc_u32 s13, s1, 0
	v_lshl_add_u64 v[60:61], v[46:47], 0, s[4:5]
	v_mov_b32_e32 v63, 0
	s_mov_b32 s15, 0
	s_movk_i32 s3, 0xf0
	s_movk_i32 s28, 0x104
	s_mov_b32 s29, 0x8000
	s_movk_i32 s30, 0x400
	s_mov_b32 s31, 0xc2fc0000
	s_brev_b32 s33, 18
	s_mov_b32 s34, 0xfe5163ab
	s_mov_b32 s35, 0x3c439041
	s_mov_b32 s36, 0xdb629599
	s_mov_b32 s37, 0xf534ddc0
	s_mov_b32 s38, 0xfc2757d1
	s_mov_b32 s39, 0x4e441529
	s_mov_b32 s40, 0xa2f9836e
	s_mov_b32 s41, 0x3fc90fda
	s_mov_b32 s42, 0x3f22f983
	s_mov_b32 s43, 0xbfc90fda
	v_mov_b32_e32 v1, 0x3c0881c4
	v_mov_b32_e32 v72, 0xbab64f3b
	s_brev_b32 s44, 1
	s_movk_i32 s45, 0x1f8
	s_mov_b64 s[16:17], 0x1000
	s_movk_i32 s46, 0x1ff
	s_movk_i32 s47, 0x2000
	s_mov_b64 s[18:19], 0x800
	s_movk_i32 s48, 0x1dff
	s_movk_i32 s49, 0x7200
	s_movk_i32 s50, 0x1400
	s_movk_i32 s51, 0x3ff
	s_movk_i32 s52, 0xfc00
	s_movk_i32 s53, 0x11ff
	s_movk_i32 s54, 0x3000
	s_movk_i32 s55, 0x6000
	s_mov_b32 s56, 0x9000
	s_mov_b32 s57, 0xc000
	s_mov_b32 s58, 0xf000
	s_mov_b32 s59, 0x12000
	s_mov_b32 s60, 0x15000
	s_mov_b32 s61, 0x18000
	s_mov_b32 s62, 0x1b000
	s_mov_b32 s63, 0x1e000
	s_mov_b32 s64, 0x21000
	s_mov_b32 s65, 0x24000
	s_mov_b32 s66, 0x27000
	s_mov_b32 s67, 0x2a000
	s_mov_b32 s68, 0x2d000
	s_movk_i32 s69, 0x280
	s_movk_i32 s70, 0xa0
	s_movk_i32 s71, 0xc00
	v_mov_b32_e32 v73, 1
	v_mov_b32_e32 v74, 0x42800000
	v_not_b32_e32 v75, 63
	v_not_b32_e32 v76, 31
	v_mov_b32_e32 v77, 0x7fc00000
	v_mov_b32_e32 v78, 0xf0
	v_mov_b32_e32 v79, 0xc00000
	s_mov_b32 s72, s2
	s_branch .LBB0_12

.LBB0_11:
	s_load_dword s4, s[12:13], 0x0
	s_waitcnt lgkmcnt(0)
	s_add_i32 s72, s4, s72
	s_and_b32 s5, s72, 0xff
	s_addk_i32 s5, 0x1300
	s_max_i32 s72, s72, s5
	s_cmpk_gt_i32 s72, 0x1320
	s_cbranch_scc1 .LBB0_67

.LBB0_68:
	s_load_dwordx2 s[24:25], s[0:1], 0x50
	s_load_dwordx2 s[26:27], s[0:1], 0xc8
	s_load_dwordx2 s[28:29], s[0:1], 0xd0
	v_lshrrev_b32_e32 v2, 4, v0
	v_and_b32_e32 v3, 15, v0
	v_lshlrev_b32_e32 v3, 4, v3
	v_lshrrev_b32_e32 v4, 3, v0
	v_and_b32_e32 v5, 7, v0
	v_mul_u32_u24_e32 v10, 0x820, v5
	v_lshl_add_u32 v10, v4, 2, v10
	v_add_u32_e32 v10, 0xf0, v10
	v_add_u32_e32 v12, 0x410, v10
	v_add_u32_e32 v11, 0x4100, v10
	v_add_u32_e32 v13, 0x4100, v12
	v_lshlrev_b32_e32 v5, 4, v5
	v_mul_u32_u24_e32 v6, 0x104, v2
	v_add_u32_e32 v6, v6, v3
	v_add_u32_e32 v6, 0xf0, v6
	v_add_u32_e32 v8, 0x2080, v6
	v_add_u32_e32 v7, 0x4100, v6
	v_add_u32_e32 v9, 0x4100, v8
	s_waitcnt lgkmcnt(0)
	s_barrier
	s_add_u32 s3, s2, 0x0
	s_cmpk_ge_u32 s3, 0x720
	s_cselect_b32 s4, 1, 0
	s_mul_i32 s5, s4, 0x720
	s_sub_u32 s5, s3, s5
	s_mul_i32 s7, s5, 575
	s_lshr_b32 s7, s7, 16
	s_mul_i32 s6, s7, 114
	s_sub_u32 s6, s5, s6
	s_mov_b32 s5, s7
	s_mul_i32 s7, s4, 0x1c80000
	s_mul_i32 s55, s5, 0x1c8000
	s_add_u32 s7, s7, s55
	s_lshl_b32 s55, s6, 8
	s_add_u32 s7, s7, s55
	s_add_u32 s32, s24, s7
	s_addc_u32 s33, s25, 0
	s_add_u32 s34, s32, 0xe4000
	s_addc_u32 s35, s33, 0
	s_mul_i32 s7, s4, 0xe40000
	s_lshl_b32 s55, s6, 17
	s_add_u32 s7, s7, s55
	s_lshl_b32 s55, s5, 7
	s_add_u32 s7, s7, s55
	s_add_u32 s36, s10, s7
	s_addc_u32 s37, s11, 0
	s_movk_i32 s38, 0x800
	s_movk_i32 s56, 0x7200
	v_mad_u32_u24 v14, v2, s56, v3
	global_load_dwordx4 v[64:67], v14, s[32:33] nt
	global_load_dwordx4 v[68:71], v14, s[34:35] nt
	s_add_u32 s3, s2, 0x100
	s_cmpk_ge_u32 s3, 0x720
	s_cselect_b32 s4, 1, 0
	s_mul_i32 s5, s4, 0x720
	s_sub_u32 s5, s3, s5
	s_mul_i32 s7, s5, 575
	s_lshr_b32 s7, s7, 16
	s_mul_i32 s6, s7, 114
	s_sub_u32 s6, s5, s6
	s_mov_b32 s5, s7
	s_mul_i32 s7, s4, 0x1c80000
	s_mul_i32 s55, s5, 0x1c8000
	s_add_u32 s7, s7, s55
	s_lshl_b32 s55, s6, 8
	s_add_u32 s7, s7, s55
	s_add_u32 s40, s24, s7
	s_addc_u32 s41, s25, 0
	s_add_u32 s42, s40, 0xe4000
	s_addc_u32 s43, s41, 0
	s_mul_i32 s7, s4, 0xe40000
	s_lshl_b32 s55, s6, 17
	s_add_u32 s7, s7, s55
	s_lshl_b32 s55, s5, 7
	s_add_u32 s7, s7, s55
	s_add_u32 s44, s10, s7
	s_addc_u32 s45, s11, 0
	s_movk_i32 s39, 0x800
	s_movk_i32 s56, 0x7200
	v_mad_u32_u24 v14, v2, s56, v3
	global_load_dwordx4 v[80:83], v14, s[40:41] nt
	global_load_dwordx4 v[84:87], v14, s[42:43] nt
	s_add_u32 s3, s2, 0x200
	s_cmpk_ge_u32 s3, 0x720
	s_cselect_b32 s4, 1, 0
	s_mul_i32 s5, s4, 0x720
	s_sub_u32 s5, s3, s5
	s_mul_i32 s7, s5, 575
	s_lshr_b32 s7, s7, 16
	s_mul_i32 s6, s7, 114
	s_sub_u32 s6, s5, s6
	s_mov_b32 s5, s7
	s_mul_i32 s7, s4, 0x1c80000
	s_mul_i32 s55, s5, 0x1c8000
	s_add_u32 s7, s7, s55
	s_lshl_b32 s55, s6, 8
	s_add_u32 s7, s7, s55
	s_add_u32 s48, s24, s7
	s_addc_u32 s49, s25, 0
	s_add_u32 s50, s48, 0xe4000
	s_addc_u32 s51, s49, 0
	s_mul_i32 s7, s4, 0xe40000
	s_lshl_b32 s55, s6, 17
	s_add_u32 s7, s7, s55
	s_lshl_b32 s55, s5, 7
	s_add_u32 s7, s7, s55
	s_add_u32 s52, s10, s7
	s_addc_u32 s53, s11, 0
	s_movk_i32 s54, 0x800
	s_movk_i32 s56, 0x7200
	v_mad_u32_u24 v14, v2, s56, v3
	global_load_dwordx4 v[88:91], v14, s[48:49] nt
	global_load_dwordx4 v[92:95], v14, s[50:51] nt
	s_waitcnt vmcnt(4)
	ds_write2_b32 v6, v64, v65 offset1:1
	ds_write2_b32 v6, v66, v67 offset0:2 offset1:3
	ds_write2_b32 v8, v68, v69 offset1:1
	ds_write2_b32 v8, v70, v71 offset0:2 offset1:3
	s_waitcnt lgkmcnt(0)
	s_barrier
	ds_read2_b32 v[96:97], v10 offset1:65
	ds_read2_b32 v[98:99], v10 offset0:130 offset1:195
	ds_read2_b32 v[100:101], v12 offset1:65
	ds_read2_b32 v[102:103], v12 offset0:130 offset1:195
	v_mad_u32_u24 v15, v4, s38, v5
	s_waitcnt lgkmcnt(0)
	v_cvt_pk_bf16_f32 v104, v96, v97
	v_cvt_pk_bf16_f32 v105, v98, v99
	v_cvt_pk_bf16_f32 v106, v100, v101
	v_cvt_pk_bf16_f32 v107, v102, v103
	global_store_dwordx4 v15, v[104:107], s[36:37]
	s_nop 1
	s_add_u32 s3, s2, 0x300
	s_cmpk_ge_u32 s3, 0x720
	s_cselect_b32 s4, 1, 0
	s_mul_i32 s5, s4, 0x720
	s_sub_u32 s5, s3, s5
	s_mul_i32 s7, s5, 575
	s_lshr_b32 s7, s7, 16
	s_mul_i32 s6, s7, 114
	s_sub_u32 s6, s5, s6
	s_mov_b32 s5, s7
	s_mul_i32 s7, s4, 0x1c80000
	s_mul_i32 s55, s5, 0x1c8000
	s_add_u32 s7, s7, s55
	s_lshl_b32 s55, s6, 8
	s_add_u32 s7, s7, s55
	s_add_u32 s32, s24, s7
	s_addc_u32 s33, s25, 0
	s_add_u32 s34, s32, 0xe4000
	s_addc_u32 s35, s33, 0
	s_mul_i32 s7, s4, 0xe40000
	s_lshl_b32 s55, s6, 17
	s_add_u32 s7, s7, s55
	s_lshl_b32 s55, s5, 7
	s_add_u32 s7, s7, s55
	s_add_u32 s36, s10, s7
	s_addc_u32 s37, s11, 0
	s_movk_i32 s38, 0x800
	s_movk_i32 s56, 0x7200
	v_mad_u32_u24 v14, v2, s56, v3
	global_load_dwordx4 v[64:67], v14, s[32:33] nt
	global_load_dwordx4 v[68:71], v14, s[34:35] nt
	s_waitcnt vmcnt(5)
	ds_write2_b32 v7, v80, v81 offset1:1
	ds_write2_b32 v7, v82, v83 offset0:2 offset1:3
	ds_write2_b32 v9, v84, v85 offset1:1
	ds_write2_b32 v9, v86, v87 offset0:2 offset1:3
	s_waitcnt lgkmcnt(0)
	s_barrier
	ds_read2_b32 v[96:97], v11 offset1:65
	ds_read2_b32 v[98:99], v11 offset0:130 offset1:195
	ds_read2_b32 v[100:101], v13 offset1:65
	ds_read2_b32 v[102:103], v13 offset0:130 offset1:195
	v_mad_u32_u24 v15, v4, s39, v5
	s_waitcnt lgkmcnt(0)
	v_cvt_pk_bf16_f32 v104, v96, v97
	v_cvt_pk_bf16_f32 v105, v98, v99
	v_cvt_pk_bf16_f32 v106, v100, v101
	v_cvt_pk_bf16_f32 v107, v102, v103
	global_store_dwordx4 v15, v[104:107], s[44:45]
	s_nop 1
	s_add_u32 s3, s2, 0x400
	s_cmpk_ge_u32 s3, 0x720
	s_cselect_b32 s4, 1, 0
	s_mul_i32 s5, s4, 0x720
	s_sub_u32 s5, s3, s5
	s_mul_i32 s7, s5, 575
	s_lshr_b32 s7, s7, 16
	s_mul_i32 s6, s7, 114
	s_sub_u32 s6, s5, s6
	s_mov_b32 s5, s7
	s_mul_i32 s7, s4, 0x1c80000
	s_mul_i32 s55, s5, 0x1c8000
	s_add_u32 s7, s7, s55
	s_lshl_b32 s55, s6, 8
	s_add_u32 s7, s7, s55
	s_add_u32 s40, s24, s7
	s_addc_u32 s41, s25, 0
	s_add_u32 s42, s40, 0xe4000
	s_addc_u32 s43, s41, 0
	s_mul_i32 s7, s4, 0xe40000
	s_lshl_b32 s55, s6, 17
	s_add_u32 s7, s7, s55
	s_lshl_b32 s55, s5, 7
	s_add_u32 s7, s7, s55
	s_add_u32 s44, s10, s7
	s_addc_u32 s45, s11, 0
	s_movk_i32 s39, 0x800
	s_movk_i32 s56, 0x7200
	v_mad_u32_u24 v14, v2, s56, v3
	global_load_dwordx4 v[80:83], v14, s[40:41] nt
	global_load_dwordx4 v[84:87], v14, s[42:43] nt
	s_waitcnt vmcnt(6)
	ds_write2_b32 v6, v88, v89 offset1:1
	ds_write2_b32 v6, v90, v91 offset0:2 offset1:3
	ds_write2_b32 v8, v92, v93 offset1:1
	ds_write2_b32 v8, v94, v95 offset0:2 offset1:3
	s_waitcnt lgkmcnt(0)
	s_barrier
	ds_read2_b32 v[96:97], v10 offset1:65
	ds_read2_b32 v[98:99], v10 offset0:130 offset1:195
	ds_read2_b32 v[100:101], v12 offset1:65
	ds_read2_b32 v[102:103], v12 offset0:130 offset1:195
	v_mad_u32_u24 v15, v4, s54, v5
	s_waitcnt lgkmcnt(0)
	v_cvt_pk_bf16_f32 v104, v96, v97
	v_cvt_pk_bf16_f32 v105, v98, v99
	v_cvt_pk_bf16_f32 v106, v100, v101
	v_cvt_pk_bf16_f32 v107, v102, v103
	global_store_dwordx4 v15, v[104:107], s[52:53]
	s_nop 1
	s_add_u32 s3, s2, 0x500
	s_cmpk_ge_u32 s3, 0x720
	s_cselect_b32 s4, 1, 0
	s_mul_i32 s5, s4, 0x720
	s_sub_u32 s5, s3, s5
	s_mul_i32 s7, s5, 575
	s_lshr_b32 s7, s7, 16
	s_mul_i32 s6, s7, 114
	s_sub_u32 s6, s5, s6
	s_mov_b32 s5, s7
	s_mul_i32 s7, s4, 0x1c80000
	s_mul_i32 s55, s5, 0x1c8000
	s_add_u32 s7, s7, s55
	s_lshl_b32 s55, s6, 8
	s_add_u32 s7, s7, s55
	s_add_u32 s48, s24, s7
	s_addc_u32 s49, s25, 0
	s_add_u32 s50, s48, 0xe4000
	s_addc_u32 s51, s49, 0
	s_mul_i32 s7, s4, 0xe40000
	s_lshl_b32 s55, s6, 17
	s_add_u32 s7, s7, s55
	s_lshl_b32 s55, s5, 7
	s_add_u32 s7, s7, s55
	s_add_u32 s52, s10, s7
	s_addc_u32 s53, s11, 0
	s_movk_i32 s54, 0x800
	s_movk_i32 s56, 0x7200
	v_mad_u32_u24 v14, v2, s56, v3
	global_load_dwordx4 v[88:91], v14, s[48:49] nt
	global_load_dwordx4 v[92:95], v14, s[50:51] nt
	s_waitcnt vmcnt(6)
	ds_write2_b32 v7, v64, v65 offset1:1
	ds_write2_b32 v7, v66, v67 offset0:2 offset1:3
	ds_write2_b32 v9, v68, v69 offset1:1
	ds_write2_b32 v9, v70, v71 offset0:2 offset1:3
	s_waitcnt lgkmcnt(0)
	s_barrier
	ds_read2_b32 v[96:97], v11 offset1:65
	ds_read2_b32 v[98:99], v11 offset0:130 offset1:195
	ds_read2_b32 v[100:101], v13 offset1:65
	ds_read2_b32 v[102:103], v13 offset0:130 offset1:195
	v_mad_u32_u24 v15, v4, s38, v5
	s_waitcnt lgkmcnt(0)
	v_cvt_pk_bf16_f32 v104, v96, v97
	v_cvt_pk_bf16_f32 v105, v98, v99
	v_cvt_pk_bf16_f32 v106, v100, v101
	v_cvt_pk_bf16_f32 v107, v102, v103
	global_store_dwordx4 v15, v[104:107], s[36:37]
	s_nop 1
	s_add_u32 s3, s2, 0x600
	s_cmpk_ge_u32 s3, 0x720
	s_cselect_b32 s4, 1, 0
	s_mul_i32 s5, s4, 0x720
	s_sub_u32 s5, s3, s5
	s_mul_i32 s7, s5, 575
	s_lshr_b32 s7, s7, 16
	s_mul_i32 s6, s7, 114
	s_sub_u32 s6, s5, s6
	s_mov_b32 s5, s7
	s_mul_i32 s7, s4, 0x1c80000
	s_mul_i32 s55, s5, 0x1c8000
	s_add_u32 s7, s7, s55
	s_lshl_b32 s55, s6, 8
	s_add_u32 s7, s7, s55
	s_add_u32 s32, s24, s7
	s_addc_u32 s33, s25, 0
	s_add_u32 s34, s32, 0xe4000
	s_addc_u32 s35, s33, 0
	s_mul_i32 s7, s4, 0xe40000
	s_lshl_b32 s55, s6, 17
	s_add_u32 s7, s7, s55
	s_lshl_b32 s55, s5, 7
	s_add_u32 s7, s7, s55
	s_add_u32 s36, s10, s7
	s_addc_u32 s37, s11, 0
	s_movk_i32 s38, 0x800
	s_movk_i32 s56, 0x7200
	v_mad_u32_u24 v14, v2, s56, v3
	global_load_dwordx4 v[64:67], v14, s[32:33] nt
	global_load_dwordx4 v[68:71], v14, s[34:35] nt
	s_waitcnt vmcnt(6)
	ds_write2_b32 v6, v80, v81 offset1:1
	ds_write2_b32 v6, v82, v83 offset0:2 offset1:3
	ds_write2_b32 v8, v84, v85 offset1:1
	ds_write2_b32 v8, v86, v87 offset0:2 offset1:3
	s_waitcnt lgkmcnt(0)
	s_barrier
	ds_read2_b32 v[96:97], v10 offset1:65
	ds_read2_b32 v[98:99], v10 offset0:130 offset1:195
	ds_read2_b32 v[100:101], v12 offset1:65
	ds_read2_b32 v[102:103], v12 offset0:130 offset1:195
	v_mad_u32_u24 v15, v4, s39, v5
	s_waitcnt lgkmcnt(0)
	v_cvt_pk_bf16_f32 v104, v96, v97
	v_cvt_pk_bf16_f32 v105, v98, v99
	v_cvt_pk_bf16_f32 v106, v100, v101
	v_cvt_pk_bf16_f32 v107, v102, v103
	global_store_dwordx4 v15, v[104:107], s[44:45]
	s_nop 1
	s_add_u32 s3, s2, 0x700
	s_cmpk_ge_u32 s3, 0x720
	s_cselect_b32 s4, 1, 0
	s_mul_i32 s5, s4, 0x720
	s_sub_u32 s5, s3, s5
	s_mul_i32 s7, s5, 575
	s_lshr_b32 s7, s7, 16
	s_mul_i32 s6, s7, 114
	s_sub_u32 s6, s5, s6
	s_mov_b32 s5, s7
	s_mul_i32 s7, s4, 0x1c80000
	s_mul_i32 s55, s5, 0x1c8000
	s_add_u32 s7, s7, s55
	s_lshl_b32 s55, s6, 8
	s_add_u32 s7, s7, s55
	s_add_u32 s40, s24, s7
	s_addc_u32 s41, s25, 0
	s_add_u32 s42, s40, 0xe4000
	s_addc_u32 s43, s41, 0
	s_mul_i32 s7, s4, 0xe40000
	s_lshl_b32 s55, s6, 17
	s_add_u32 s7, s7, s55
	s_lshl_b32 s55, s5, 7
	s_add_u32 s7, s7, s55
	s_add_u32 s44, s10, s7
	s_addc_u32 s45, s11, 0
	s_movk_i32 s39, 0x800
	s_movk_i32 s56, 0x7200
	v_mad_u32_u24 v14, v2, s56, v3
	global_load_dwordx4 v[80:83], v14, s[40:41] nt
	global_load_dwordx4 v[84:87], v14, s[42:43] nt
	s_waitcnt vmcnt(6)
	ds_write2_b32 v7, v88, v89 offset1:1
	ds_write2_b32 v7, v90, v91 offset0:2 offset1:3
	ds_write2_b32 v9, v92, v93 offset1:1
	ds_write2_b32 v9, v94, v95 offset0:2 offset1:3
	s_waitcnt lgkmcnt(0)
	s_barrier
	ds_read2_b32 v[96:97], v11 offset1:65
	ds_read2_b32 v[98:99], v11 offset0:130 offset1:195
	ds_read2_b32 v[100:101], v13 offset1:65
	ds_read2_b32 v[102:103], v13 offset0:130 offset1:195
	v_mad_u32_u24 v15, v4, s54, v5
	s_waitcnt lgkmcnt(0)
	v_cvt_pk_bf16_f32 v104, v96, v97
	v_cvt_pk_bf16_f32 v105, v98, v99
	v_cvt_pk_bf16_f32 v106, v100, v101
	v_cvt_pk_bf16_f32 v107, v102, v103
	global_store_dwordx4 v15, v[104:107], s[52:53]
	s_nop 1
	s_add_u32 s3, s2, 0x800
	s_cmpk_ge_u32 s3, 0x720
	s_cselect_b32 s4, 1, 0
	s_mul_i32 s5, s4, 0x720
	s_sub_u32 s5, s3, s5
	s_mul_i32 s7, s5, 575
	s_lshr_b32 s7, s7, 16
	s_mul_i32 s6, s7, 114
	s_sub_u32 s6, s5, s6
	s_mov_b32 s5, s7
	s_mul_i32 s7, s4, 0x1c80000
	s_mul_i32 s55, s5, 0x1c8000
	s_add_u32 s7, s7, s55
	s_lshl_b32 s55, s6, 8
	s_add_u32 s7, s7, s55
	s_add_u32 s48, s24, s7
	s_addc_u32 s49, s25, 0
	s_add_u32 s50, s48, 0xe4000
	s_addc_u32 s51, s49, 0
	s_mul_i32 s7, s4, 0xe40000
	s_lshl_b32 s55, s6, 17
	s_add_u32 s7, s7, s55
	s_lshl_b32 s55, s5, 7
	s_add_u32 s7, s7, s55
	s_add_u32 s52, s10, s7
	s_addc_u32 s53, s11, 0
	s_movk_i32 s54, 0x800
	s_movk_i32 s56, 0x7200
	v_mad_u32_u24 v14, v2, s56, v3
	global_load_dwordx4 v[88:91], v14, s[48:49] nt
	global_load_dwordx4 v[92:95], v14, s[50:51] nt
	s_waitcnt vmcnt(6)
	ds_write2_b32 v6, v64, v65 offset1:1
	ds_write2_b32 v6, v66, v67 offset0:2 offset1:3
	ds_write2_b32 v8, v68, v69 offset1:1
	ds_write2_b32 v8, v70, v71 offset0:2 offset1:3
	s_waitcnt lgkmcnt(0)
	s_barrier
	ds_read2_b32 v[96:97], v10 offset1:65
	ds_read2_b32 v[98:99], v10 offset0:130 offset1:195
	ds_read2_b32 v[100:101], v12 offset1:65
	ds_read2_b32 v[102:103], v12 offset0:130 offset1:195
	v_mad_u32_u24 v15, v4, s38, v5
	s_waitcnt lgkmcnt(0)
	v_cvt_pk_bf16_f32 v104, v96, v97
	v_cvt_pk_bf16_f32 v105, v98, v99
	v_cvt_pk_bf16_f32 v106, v100, v101
	v_cvt_pk_bf16_f32 v107, v102, v103
	global_store_dwordx4 v15, v[104:107], s[36:37]
	s_nop 1
	s_add_u32 s3, s2, 0x900
	s_cmpk_ge_u32 s3, 0x720
	s_cselect_b32 s4, 1, 0
	s_mul_i32 s5, s4, 0x720
	s_sub_u32 s5, s3, s5
	s_mul_i32 s7, s5, 575
	s_lshr_b32 s7, s7, 16
	s_mul_i32 s6, s7, 114
	s_sub_u32 s6, s5, s6
	s_mov_b32 s5, s7
	s_mul_i32 s7, s4, 0x1c80000
	s_mul_i32 s55, s5, 0x1c8000
	s_add_u32 s7, s7, s55
	s_lshl_b32 s55, s6, 8
	s_add_u32 s7, s7, s55
	s_add_u32 s32, s24, s7
	s_addc_u32 s33, s25, 0
	s_add_u32 s34, s32, 0xe4000
	s_addc_u32 s35, s33, 0
	s_mul_i32 s7, s4, 0xe40000
	s_lshl_b32 s55, s6, 17
	s_add_u32 s7, s7, s55
	s_lshl_b32 s55, s5, 7
	s_add_u32 s7, s7, s55
	s_add_u32 s36, s10, s7
	s_addc_u32 s37, s11, 0
	s_movk_i32 s38, 0x800
	s_movk_i32 s56, 0x7200
	v_mad_u32_u24 v14, v2, s56, v3
	global_load_dwordx4 v[64:67], v14, s[32:33] nt
	global_load_dwordx4 v[68:71], v14, s[34:35] nt
	s_waitcnt vmcnt(6)
	ds_write2_b32 v7, v80, v81 offset1:1
	ds_write2_b32 v7, v82, v83 offset0:2 offset1:3
	ds_write2_b32 v9, v84, v85 offset1:1
	ds_write2_b32 v9, v86, v87 offset0:2 offset1:3
	s_waitcnt lgkmcnt(0)
	s_barrier
	ds_read2_b32 v[96:97], v11 offset1:65
	ds_read2_b32 v[98:99], v11 offset0:130 offset1:195
	ds_read2_b32 v[100:101], v13 offset1:65
	ds_read2_b32 v[102:103], v13 offset0:130 offset1:195
	v_mad_u32_u24 v15, v4, s39, v5
	s_waitcnt lgkmcnt(0)
	v_cvt_pk_bf16_f32 v104, v96, v97
	v_cvt_pk_bf16_f32 v105, v98, v99
	v_cvt_pk_bf16_f32 v106, v100, v101
	v_cvt_pk_bf16_f32 v107, v102, v103
	global_store_dwordx4 v15, v[104:107], s[44:45]
	s_nop 1
	s_add_u32 s3, s2, 0xa00
	s_cmpk_ge_u32 s3, 0x720
	s_cselect_b32 s4, 1, 0
	s_mul_i32 s5, s4, 0x720
	s_sub_u32 s5, s3, s5
	s_mul_i32 s7, s5, 575
	s_lshr_b32 s7, s7, 16
	s_mul_i32 s6, s7, 114
	s_sub_u32 s6, s5, s6
	s_mov_b32 s5, s7
	s_mul_i32 s7, s4, 0x1c80000
	s_mul_i32 s55, s5, 0x1c8000
	s_add_u32 s7, s7, s55
	s_lshl_b32 s55, s6, 8
	s_add_u32 s7, s7, s55
	s_add_u32 s40, s24, s7
	s_addc_u32 s41, s25, 0
	s_add_u32 s42, s40, 0xe4000
	s_addc_u32 s43, s41, 0
	s_mul_i32 s7, s4, 0xe40000
	s_lshl_b32 s55, s6, 17
	s_add_u32 s7, s7, s55
	s_lshl_b32 s55, s5, 7
	s_add_u32 s7, s7, s55
	s_add_u32 s44, s10, s7
	s_addc_u32 s45, s11, 0
	s_movk_i32 s39, 0x800
	s_movk_i32 s56, 0x7200
	v_mad_u32_u24 v14, v2, s56, v3
	global_load_dwordx4 v[80:83], v14, s[40:41] nt
	global_load_dwordx4 v[84:87], v14, s[42:43] nt
	s_waitcnt vmcnt(6)
	ds_write2_b32 v6, v88, v89 offset1:1
	ds_write2_b32 v6, v90, v91 offset0:2 offset1:3
	ds_write2_b32 v8, v92, v93 offset1:1
	ds_write2_b32 v8, v94, v95 offset0:2 offset1:3
	s_waitcnt lgkmcnt(0)
	s_barrier
	ds_read2_b32 v[96:97], v10 offset1:65
	ds_read2_b32 v[98:99], v10 offset0:130 offset1:195
	ds_read2_b32 v[100:101], v12 offset1:65
	ds_read2_b32 v[102:103], v12 offset0:130 offset1:195
	v_mad_u32_u24 v15, v4, s54, v5
	s_waitcnt lgkmcnt(0)
	v_cvt_pk_bf16_f32 v104, v96, v97
	v_cvt_pk_bf16_f32 v105, v98, v99
	v_cvt_pk_bf16_f32 v106, v100, v101
	v_cvt_pk_bf16_f32 v107, v102, v103
	global_store_dwordx4 v15, v[104:107], s[52:53]
	s_nop 1
	s_add_u32 s3, s2, 0xb00
	s_cmpk_ge_u32 s3, 0x720
	s_cselect_b32 s4, 1, 0
	s_mul_i32 s5, s4, 0x720
	s_sub_u32 s5, s3, s5
	s_mul_i32 s7, s5, 575
	s_lshr_b32 s7, s7, 16
	s_mul_i32 s6, s7, 114
	s_sub_u32 s6, s5, s6
	s_mov_b32 s5, s7
	s_mul_i32 s7, s4, 0x1c80000
	s_mul_i32 s55, s5, 0x1c8000
	s_add_u32 s7, s7, s55
	s_lshl_b32 s55, s6, 8
	s_add_u32 s7, s7, s55
	s_add_u32 s48, s24, s7
	s_addc_u32 s49, s25, 0
	s_add_u32 s50, s48, 0xe4000
	s_addc_u32 s51, s49, 0
	s_mul_i32 s7, s4, 0xe40000
	s_lshl_b32 s55, s6, 17
	s_add_u32 s7, s7, s55
	s_lshl_b32 s55, s5, 7
	s_add_u32 s7, s7, s55
	s_add_u32 s52, s10, s7
	s_addc_u32 s53, s11, 0
	s_movk_i32 s54, 0x800
	s_movk_i32 s56, 0x7200
	v_mad_u32_u24 v14, v2, s56, v3
	global_load_dwordx4 v[88:91], v14, s[48:49] nt
	global_load_dwordx4 v[92:95], v14, s[50:51] nt
	s_waitcnt vmcnt(6)
	ds_write2_b32 v7, v64, v65 offset1:1
	ds_write2_b32 v7, v66, v67 offset0:2 offset1:3
	ds_write2_b32 v9, v68, v69 offset1:1
	ds_write2_b32 v9, v70, v71 offset0:2 offset1:3
	s_waitcnt lgkmcnt(0)
	s_barrier
	ds_read2_b32 v[96:97], v11 offset1:65
	ds_read2_b32 v[98:99], v11 offset0:130 offset1:195
	ds_read2_b32 v[100:101], v13 offset1:65
	ds_read2_b32 v[102:103], v13 offset0:130 offset1:195
	v_mad_u32_u24 v15, v4, s38, v5
	s_waitcnt lgkmcnt(0)
	v_cvt_pk_bf16_f32 v104, v96, v97
	v_cvt_pk_bf16_f32 v105, v98, v99
	v_cvt_pk_bf16_f32 v106, v100, v101
	v_cvt_pk_bf16_f32 v107, v102, v103
	global_store_dwordx4 v15, v[104:107], s[36:37]
	s_nop 1
	s_add_u32 s3, s2, 0xc00
	s_cmpk_ge_u32 s3, 0x720
	s_cselect_b32 s4, 1, 0
	s_mul_i32 s5, s4, 0x720
	s_sub_u32 s5, s3, s5
	s_mul_i32 s7, s5, 575
	s_lshr_b32 s7, s7, 16
	s_mul_i32 s6, s7, 114
	s_sub_u32 s6, s5, s6
	s_mov_b32 s5, s7
	s_mul_i32 s7, s4, 0x1c80000
	s_mul_i32 s55, s5, 0x1c8000
	s_add_u32 s7, s7, s55
	s_lshl_b32 s55, s6, 8
	s_add_u32 s7, s7, s55
	s_add_u32 s32, s24, s7
	s_addc_u32 s33, s25, 0
	s_add_u32 s34, s32, 0xe4000
	s_addc_u32 s35, s33, 0
	s_mul_i32 s7, s4, 0xe40000
	s_lshl_b32 s55, s6, 17
	s_add_u32 s7, s7, s55
	s_lshl_b32 s55, s5, 7
	s_add_u32 s7, s7, s55
	s_add_u32 s36, s10, s7
	s_addc_u32 s37, s11, 0
	s_movk_i32 s38, 0x800
	s_movk_i32 s56, 0x7200
	v_mad_u32_u24 v14, v2, s56, v3
	global_load_dwordx4 v[64:67], v14, s[32:33] nt
	global_load_dwordx4 v[68:71], v14, s[34:35] nt
	s_waitcnt vmcnt(6)
	ds_write2_b32 v6, v80, v81 offset1:1
	ds_write2_b32 v6, v82, v83 offset0:2 offset1:3
	ds_write2_b32 v8, v84, v85 offset1:1
	ds_write2_b32 v8, v86, v87 offset0:2 offset1:3
	s_waitcnt lgkmcnt(0)
	s_barrier
	ds_read2_b32 v[96:97], v10 offset1:65
	ds_read2_b32 v[98:99], v10 offset0:130 offset1:195
	ds_read2_b32 v[100:101], v12 offset1:65
	ds_read2_b32 v[102:103], v12 offset0:130 offset1:195
	v_mad_u32_u24 v15, v4, s39, v5
	s_waitcnt lgkmcnt(0)
	v_cvt_pk_bf16_f32 v104, v96, v97
	v_cvt_pk_bf16_f32 v105, v98, v99
	v_cvt_pk_bf16_f32 v106, v100, v101
	v_cvt_pk_bf16_f32 v107, v102, v103
	global_store_dwordx4 v15, v[104:107], s[44:45]
	s_nop 1
	s_add_u32 s3, s2, 0xd00
	s_cmpk_ge_u32 s3, 0x720
	s_cselect_b32 s4, 1, 0
	s_mul_i32 s5, s4, 0x720
	s_sub_u32 s5, s3, s5
	s_mul_i32 s7, s5, 575
	s_lshr_b32 s7, s7, 16
	s_mul_i32 s6, s7, 114
	s_sub_u32 s6, s5, s6
	s_mov_b32 s5, s7
	s_mul_i32 s7, s4, 0x1c80000
	s_mul_i32 s55, s5, 0x1c8000
	s_add_u32 s7, s7, s55
	s_lshl_b32 s55, s6, 8
	s_add_u32 s7, s7, s55
	s_add_u32 s40, s24, s7
	s_addc_u32 s41, s25, 0
	s_add_u32 s42, s40, 0xe4000
	s_addc_u32 s43, s41, 0
	s_mul_i32 s7, s4, 0xe40000
	s_lshl_b32 s55, s6, 17
	s_add_u32 s7, s7, s55
	s_lshl_b32 s55, s5, 7
	s_add_u32 s7, s7, s55
	s_add_u32 s44, s10, s7
	s_addc_u32 s45, s11, 0
	s_movk_i32 s39, 0x800
	s_movk_i32 s56, 0x7200
	v_mad_u32_u24 v14, v2, s56, v3
	global_load_dwordx4 v[80:83], v14, s[40:41] nt
	global_load_dwordx4 v[84:87], v14, s[42:43] nt
	s_waitcnt vmcnt(6)
	ds_write2_b32 v7, v88, v89 offset1:1
	ds_write2_b32 v7, v90, v91 offset0:2 offset1:3
	ds_write2_b32 v9, v92, v93 offset1:1
	ds_write2_b32 v9, v94, v95 offset0:2 offset1:3
	s_waitcnt lgkmcnt(0)
	s_barrier
	ds_read2_b32 v[96:97], v11 offset1:65
	ds_read2_b32 v[98:99], v11 offset0:130 offset1:195
	ds_read2_b32 v[100:101], v13 offset1:65
	ds_read2_b32 v[102:103], v13 offset0:130 offset1:195
	v_mad_u32_u24 v15, v4, s54, v5
	s_waitcnt lgkmcnt(0)
	v_cvt_pk_bf16_f32 v104, v96, v97
	v_cvt_pk_bf16_f32 v105, v98, v99
	v_cvt_pk_bf16_f32 v106, v100, v101
	v_cvt_pk_bf16_f32 v107, v102, v103
	global_store_dwordx4 v15, v[104:107], s[52:53]
	s_nop 1
	s_add_u32 s3, s2, 0xe00
	s_cmpk_lt_u32 s2, 0x40
	s_cbranch_scc0 .Ls0c_b14
	s_cmpk_ge_u32 s3, 0x720
	s_cselect_b32 s4, 1, 0
	s_mul_i32 s5, s4, 0x720
	s_sub_u32 s5, s3, s5
	s_mul_i32 s7, s5, 575
	s_lshr_b32 s7, s7, 16
	s_mul_i32 s6, s7, 114
	s_sub_u32 s6, s5, s6
	s_mov_b32 s5, s7
	s_mul_i32 s7, s4, 0x1c80000
	s_mul_i32 s55, s5, 0x1c8000
	s_add_u32 s7, s7, s55
	s_lshl_b32 s55, s6, 8
	s_add_u32 s7, s7, s55
	s_add_u32 s48, s24, s7
	s_addc_u32 s49, s25, 0
	s_add_u32 s50, s48, 0xe4000
	s_addc_u32 s51, s49, 0
	s_mul_i32 s7, s4, 0xe40000
	s_lshl_b32 s55, s6, 17
	s_add_u32 s7, s7, s55
	s_lshl_b32 s55, s5, 7
	s_add_u32 s7, s7, s55
	s_add_u32 s52, s10, s7
	s_addc_u32 s53, s11, 0
	s_movk_i32 s54, 0x800
	s_movk_i32 s56, 0x7200
	s_branch .Ls0c_j14
.Ls0c_b14:
	s_sub_u32 s5, s3, 0xe40
	s_lshr_b32 s4, s5, 6
	s_and_b32 s5, s5, 63
	s_and_b32 s6, s5, 15
	s_lshr_b32 s5, s5, 4
	s_mul_i32 s7, s4, 0x100000
	s_mul_i32 s55, s5, 0x40000
	s_add_u32 s7, s7, s55
	s_lshl_b32 s55, s6, 8
	s_add_u32 s7, s7, s55
	s_add_u32 s48, s26, s7
	s_addc_u32 s49, s27, 0
	s_add_u32 s50, s48, 0x20000
	s_addc_u32 s51, s49, 0
	s_mul_i32 s7, s4, 0x80000
	s_lshl_b32 s55, s6, 15
	s_add_u32 s7, s7, s55
	s_lshl_b32 s55, s5, 7
	s_add_u32 s7, s7, s55
	s_add_u32 s7, s7, 0x1c80000
	s_add_u32 s52, s10, s7
	s_addc_u32 s53, s11, 0
	s_movk_i32 s54, 0x200
	s_movk_i32 s56, 0x1000
.Ls0c_j14:
	v_mad_u32_u24 v14, v2, s56, v3
	global_load_dwordx4 v[88:91], v14, s[48:49] nt
	global_load_dwordx4 v[92:95], v14, s[50:51] nt
	s_waitcnt vmcnt(6)
	ds_write2_b32 v6, v64, v65 offset1:1
	ds_write2_b32 v6, v66, v67 offset0:2 offset1:3
	ds_write2_b32 v8, v68, v69 offset1:1
	ds_write2_b32 v8, v70, v71 offset0:2 offset1:3
	s_waitcnt lgkmcnt(0)
	s_barrier
	ds_read2_b32 v[96:97], v10 offset1:65
	ds_read2_b32 v[98:99], v10 offset0:130 offset1:195
	ds_read2_b32 v[100:101], v12 offset1:65
	ds_read2_b32 v[102:103], v12 offset0:130 offset1:195
	v_mad_u32_u24 v15, v4, s38, v5
	s_waitcnt lgkmcnt(0)
	v_cvt_pk_bf16_f32 v104, v96, v97
	v_cvt_pk_bf16_f32 v105, v98, v99
	v_cvt_pk_bf16_f32 v106, v100, v101
	v_cvt_pk_bf16_f32 v107, v102, v103
	global_store_dwordx4 v15, v[104:107], s[36:37]
	s_nop 1
	s_add_u32 s3, s2, 0xf00
	s_sub_u32 s5, s3, 0xe40
	s_lshr_b32 s4, s5, 6
	s_and_b32 s5, s5, 63
	s_and_b32 s6, s5, 15
	s_lshr_b32 s5, s5, 4
	s_mul_i32 s7, s4, 0x100000
	s_mul_i32 s55, s5, 0x40000
	s_add_u32 s7, s7, s55
	s_lshl_b32 s55, s6, 8
	s_add_u32 s7, s7, s55
	s_add_u32 s32, s26, s7
	s_addc_u32 s33, s27, 0
	s_add_u32 s34, s32, 0x20000
	s_addc_u32 s35, s33, 0
	s_mul_i32 s7, s4, 0x80000
	s_lshl_b32 s55, s6, 15
	s_add_u32 s7, s7, s55
	s_lshl_b32 s55, s5, 7
	s_add_u32 s7, s7, s55
	s_add_u32 s7, s7, 0x1c80000
	s_add_u32 s36, s10, s7
	s_addc_u32 s37, s11, 0
	s_movk_i32 s38, 0x200
	s_movk_i32 s56, 0x1000
	v_mad_u32_u24 v14, v2, s56, v3
	global_load_dwordx4 v[64:67], v14, s[32:33] nt
	global_load_dwordx4 v[68:71], v14, s[34:35] nt
	s_waitcnt vmcnt(6)
	ds_write2_b32 v7, v80, v81 offset1:1
	ds_write2_b32 v7, v82, v83 offset0:2 offset1:3
	ds_write2_b32 v9, v84, v85 offset1:1
	ds_write2_b32 v9, v86, v87 offset0:2 offset1:3
	s_waitcnt lgkmcnt(0)
	s_barrier
	ds_read2_b32 v[96:97], v11 offset1:65
	ds_read2_b32 v[98:99], v11 offset0:130 offset1:195
	ds_read2_b32 v[100:101], v13 offset1:65
	ds_read2_b32 v[102:103], v13 offset0:130 offset1:195
	v_mad_u32_u24 v15, v4, s39, v5
	s_waitcnt lgkmcnt(0)
	v_cvt_pk_bf16_f32 v104, v96, v97
	v_cvt_pk_bf16_f32 v105, v98, v99
	v_cvt_pk_bf16_f32 v106, v100, v101
	v_cvt_pk_bf16_f32 v107, v102, v103
	global_store_dwordx4 v15, v[104:107], s[44:45]
	s_nop 1
	s_add_u32 s3, s2, 0x1000
	s_cmpk_lt_u32 s2, 0x40
	s_cbranch_scc0 .Ls0c_b16
	s_sub_u32 s5, s3, 0xe40
	s_lshr_b32 s4, s5, 6
	s_and_b32 s5, s5, 63
	s_and_b32 s6, s5, 15
	s_lshr_b32 s5, s5, 4
	s_mul_i32 s7, s4, 0x100000
	s_mul_i32 s55, s5, 0x40000
	s_add_u32 s7, s7, s55
	s_lshl_b32 s55, s6, 8
	s_add_u32 s7, s7, s55
	s_add_u32 s40, s26, s7
	s_addc_u32 s41, s27, 0
	s_add_u32 s42, s40, 0x20000
	s_addc_u32 s43, s41, 0
	s_mul_i32 s7, s4, 0x80000
	s_lshl_b32 s55, s6, 15
	s_add_u32 s7, s7, s55
	s_lshl_b32 s55, s5, 7
	s_add_u32 s7, s7, s55
	s_add_u32 s7, s7, 0x1c80000
	s_add_u32 s44, s10, s7
	s_addc_u32 s45, s11, 0
	s_movk_i32 s39, 0x200
	s_movk_i32 s56, 0x1000
	s_branch .Ls0c_j16
.Ls0c_b16:
	s_sub_u32 s5, s3, 0x1040
	s_lshr_b32 s4, s5, 8
	s_and_b32 s5, s5, 255
	s_and_b32 s6, s5, 15
	s_lshr_b32 s5, s5, 4
	s_mul_i32 s7, s4, 0x400000
	s_mul_i32 s55, s5, 0x40000
	s_add_u32 s7, s7, s55
	s_lshl_b32 s55, s6, 8
	s_add_u32 s7, s7, s55
	s_add_u32 s40, s28, s7
	s_addc_u32 s41, s29, 0
	s_add_u32 s42, s40, 0x20000
	s_addc_u32 s43, s41, 0
	s_mul_i32 s7, s4, 0x200000
	s_lshl_b32 s55, s6, 17
	s_add_u32 s7, s7, s55
	s_lshl_b32 s55, s5, 7
	s_add_u32 s7, s7, s55
	s_add_u32 s7, s7, 0x2080000
	s_add_u32 s44, s10, s7
	s_addc_u32 s45, s11, 0
	s_movk_i32 s39, 0x800
	s_movk_i32 s56, 0x1000
.Ls0c_j16:
	v_mad_u32_u24 v14, v2, s56, v3
	global_load_dwordx4 v[80:83], v14, s[40:41] nt
	global_load_dwordx4 v[84:87], v14, s[42:43] nt
	s_waitcnt vmcnt(6)
	ds_write2_b32 v6, v88, v89 offset1:1
	ds_write2_b32 v6, v90, v91 offset0:2 offset1:3
	ds_write2_b32 v8, v92, v93 offset1:1
	ds_write2_b32 v8, v94, v95 offset0:2 offset1:3
	s_waitcnt lgkmcnt(0)
	s_barrier
	ds_read2_b32 v[96:97], v10 offset1:65
	ds_read2_b32 v[98:99], v10 offset0:130 offset1:195
	ds_read2_b32 v[100:101], v12 offset1:65
	ds_read2_b32 v[102:103], v12 offset0:130 offset1:195
	v_mad_u32_u24 v15, v4, s54, v5
	s_waitcnt lgkmcnt(0)
	v_cvt_pk_bf16_f32 v104, v96, v97
	v_cvt_pk_bf16_f32 v105, v98, v99
	v_cvt_pk_bf16_f32 v106, v100, v101
	v_cvt_pk_bf16_f32 v107, v102, v103
	global_store_dwordx4 v15, v[104:107], s[52:53]
	s_nop 1
	s_add_u32 s3, s2, 0x1100
	s_sub_u32 s5, s3, 0x1040
	s_lshr_b32 s4, s5, 8
	s_and_b32 s5, s5, 255
	s_and_b32 s6, s5, 15
	s_lshr_b32 s5, s5, 4
	s_mul_i32 s7, s4, 0x400000
	s_mul_i32 s55, s5, 0x40000
	s_add_u32 s7, s7, s55
	s_lshl_b32 s55, s6, 8
	s_add_u32 s7, s7, s55
	s_add_u32 s48, s28, s7
	s_addc_u32 s49, s29, 0
	s_add_u32 s50, s48, 0x20000
	s_addc_u32 s51, s49, 0
	s_mul_i32 s7, s4, 0x200000
	s_lshl_b32 s55, s6, 17
	s_add_u32 s7, s7, s55
	s_lshl_b32 s55, s5, 7
	s_add_u32 s7, s7, s55
	s_add_u32 s7, s7, 0x2080000
	s_add_u32 s52, s10, s7
	s_addc_u32 s53, s11, 0
	s_movk_i32 s54, 0x800
	s_movk_i32 s56, 0x1000
	v_mad_u32_u24 v14, v2, s56, v3
	global_load_dwordx4 v[88:91], v14, s[48:49] nt
	global_load_dwordx4 v[92:95], v14, s[50:51] nt
	s_waitcnt vmcnt(6)
	ds_write2_b32 v7, v64, v65 offset1:1
	ds_write2_b32 v7, v66, v67 offset0:2 offset1:3
	ds_write2_b32 v9, v68, v69 offset1:1
	ds_write2_b32 v9, v70, v71 offset0:2 offset1:3
	s_waitcnt lgkmcnt(0)
	s_barrier
	ds_read2_b32 v[96:97], v11 offset1:65
	ds_read2_b32 v[98:99], v11 offset0:130 offset1:195
	ds_read2_b32 v[100:101], v13 offset1:65
	ds_read2_b32 v[102:103], v13 offset0:130 offset1:195
	v_mad_u32_u24 v15, v4, s38, v5
	s_waitcnt lgkmcnt(0)
	v_cvt_pk_bf16_f32 v104, v96, v97
	v_cvt_pk_bf16_f32 v105, v98, v99
	v_cvt_pk_bf16_f32 v106, v100, v101
	v_cvt_pk_bf16_f32 v107, v102, v103
	global_store_dwordx4 v15, v[104:107], s[36:37]
	s_nop 1
	s_add_u32 s3, s2, 0x1200
	s_cmpk_lt_u32 s2, 0x40
	s_cbranch_scc0 .Ls0c_b18
	s_sub_u32 s5, s3, 0x1040
	s_lshr_b32 s4, s5, 8
	s_and_b32 s5, s5, 255
	s_and_b32 s6, s5, 15
	s_lshr_b32 s5, s5, 4
	s_mul_i32 s7, s4, 0x400000
	s_mul_i32 s55, s5, 0x40000
	s_add_u32 s7, s7, s55
	s_lshl_b32 s55, s6, 8
	s_add_u32 s7, s7, s55
	s_add_u32 s32, s28, s7
	s_addc_u32 s33, s29, 0
	s_add_u32 s34, s32, 0x20000
	s_addc_u32 s35, s33, 0
	s_mul_i32 s7, s4, 0x200000
	s_lshl_b32 s55, s6, 17
	s_add_u32 s7, s7, s55
	s_lshl_b32 s55, s5, 7
	s_add_u32 s7, s7, s55
	s_add_u32 s7, s7, 0x2080000
	s_add_u32 s36, s10, s7
	s_addc_u32 s37, s11, 0
	s_movk_i32 s38, 0x800
	s_movk_i32 s56, 0x1000
	s_branch .Ls0c_j18
.Ls0c_b18:
	s_sub_u32 s3, s3, 0x100
	s_sub_u32 s5, s3, 0x1040
	s_lshr_b32 s4, s5, 8
	s_and_b32 s5, s5, 255
	s_and_b32 s6, s5, 15
	s_lshr_b32 s5, s5, 4
	s_mul_i32 s7, s4, 0x400000
	s_mul_i32 s55, s5, 0x40000
	s_add_u32 s7, s7, s55
	s_lshl_b32 s55, s6, 8
	s_add_u32 s7, s7, s55
	s_add_u32 s32, s28, s7
	s_addc_u32 s33, s29, 0
	s_add_u32 s34, s32, 0x20000
	s_addc_u32 s35, s33, 0
	s_mul_i32 s7, s4, 0x200000
	s_lshl_b32 s55, s6, 17
	s_add_u32 s7, s7, s55
	s_lshl_b32 s55, s5, 7
	s_add_u32 s7, s7, s55
	s_add_u32 s7, s7, 0x2080000
	s_add_u32 s36, s10, s7
	s_addc_u32 s37, s11, 0
	s_movk_i32 s38, 0x800
	s_movk_i32 s56, 0x1000
.Ls0c_j18:
	v_mad_u32_u24 v14, v2, s56, v3
	global_load_dwordx4 v[64:67], v14, s[32:33] nt
	global_load_dwordx4 v[68:71], v14, s[34:35] nt
	s_waitcnt vmcnt(6)
	ds_write2_b32 v6, v80, v81 offset1:1
	ds_write2_b32 v6, v82, v83 offset0:2 offset1:3
	ds_write2_b32 v8, v84, v85 offset1:1
	ds_write2_b32 v8, v86, v87 offset0:2 offset1:3
	s_waitcnt lgkmcnt(0)
	s_barrier
	ds_read2_b32 v[96:97], v10 offset1:65
	ds_read2_b32 v[98:99], v10 offset0:130 offset1:195
	ds_read2_b32 v[100:101], v12 offset1:65
	ds_read2_b32 v[102:103], v12 offset0:130 offset1:195
	v_mad_u32_u24 v15, v4, s39, v5
	s_waitcnt lgkmcnt(0)
	v_cvt_pk_bf16_f32 v104, v96, v97
	v_cvt_pk_bf16_f32 v105, v98, v99
	v_cvt_pk_bf16_f32 v106, v100, v101
	v_cvt_pk_bf16_f32 v107, v102, v103
	global_store_dwordx4 v15, v[104:107], s[44:45]
	s_nop 1
	s_waitcnt vmcnt(4)
	ds_write2_b32 v7, v88, v89 offset1:1
	ds_write2_b32 v7, v90, v91 offset0:2 offset1:3
	ds_write2_b32 v9, v92, v93 offset1:1
	ds_write2_b32 v9, v94, v95 offset0:2 offset1:3
	s_waitcnt lgkmcnt(0)
	s_barrier
	ds_read2_b32 v[96:97], v11 offset1:65
	ds_read2_b32 v[98:99], v11 offset0:130 offset1:195
	ds_read2_b32 v[100:101], v13 offset1:65
	ds_read2_b32 v[102:103], v13 offset0:130 offset1:195
	v_mad_u32_u24 v15, v4, s54, v5
	s_waitcnt lgkmcnt(0)
	v_cvt_pk_bf16_f32 v104, v96, v97
	v_cvt_pk_bf16_f32 v105, v98, v99
	v_cvt_pk_bf16_f32 v106, v100, v101
	v_cvt_pk_bf16_f32 v107, v102, v103
	global_store_dwordx4 v15, v[104:107], s[52:53]
	s_nop 1
	s_waitcnt vmcnt(2)
	ds_write2_b32 v6, v64, v65 offset1:1
	ds_write2_b32 v6, v66, v67 offset0:2 offset1:3
	ds_write2_b32 v8, v68, v69 offset1:1
	ds_write2_b32 v8, v70, v71 offset0:2 offset1:3
	s_waitcnt lgkmcnt(0)
	s_barrier
	ds_read2_b32 v[96:97], v10 offset1:65
	ds_read2_b32 v[98:99], v10 offset0:130 offset1:195
	ds_read2_b32 v[100:101], v12 offset1:65
	ds_read2_b32 v[102:103], v12 offset0:130 offset1:195
	v_mad_u32_u24 v15, v4, s38, v5
	s_waitcnt lgkmcnt(0)
	v_cvt_pk_bf16_f32 v104, v96, v97
	v_cvt_pk_bf16_f32 v105, v98, v99
	v_cvt_pk_bf16_f32 v106, v100, v101
	v_cvt_pk_bf16_f32 v107, v102, v103
	global_store_dwordx4 v15, v[104:107], s[36:37]
	s_nop 1
	s_waitcnt vmcnt(0)
	s_barrier
	v_mov_b32_e32 v1, v0
	s_nop 0
	v_cmp_eq_u32_e32 vcc, 0, v1
	s_and_saveexec_b64 s[4:5], vcc
	s_cbranch_execz .LBB0_82
	s_mov_b64 s[6:7], 0x24a0040
	v_lshl_add_u64 v[2:3], v[46:47], 0, s[6:7]
	s_mov_b32 s3, 0x400001
	s_mov_b64 s[6:7], 0
	s_movk_i32 s24, 0x60
	s_branch .LBB0_75
